# v19 plus static s_setprio 1 for waves 4-7 during the HGRN2 scan phase (they carry the inter + o-tile MFMA stages)
# baseline (speedup 1.0000x reference)
; #define LAS __attribute__((address_space(3)))
; __device__ __forceinline__ void scan_item(const Ctx& C, int b, int h, int half, const bf16* HQ, const bf16* LOGF, bf16* HI  , float* SSQ) {
;     int tid = threadIdx.x; asm volatile("" : "+v"(tid));
;     const int lane = tid & 63, r = lane & 31, hh = lane >> 5, w = __builtin_amdgcn_readfirstlane(tid >> 6);
;     LAS unsigned char* L = C.lds;
;     const size_t tokb = (size_t)b * SEQ;
;     for (int i = tid; i < 64 * P128 / 2; i += NTHR) ((LAS unsigned*)(L + O_ST))[i] = 0u;
;     f32x16 sacc;
; #pragma unroll
;     for (int i = 0; i < 16; ++i) sacc[i] = 0.f;
;     const int kt_own = w >> 1, di_own = w & 1;
;     const int vt_t = tid >> 3, vt_d = (tid & 7) * 8;
;     v4u rq[2], rl[2], rv;
; __device__ __forceinline__ void scan_phase(const Ctx& C, const bf16* HQ, const bf16* LOGF, bf16* HI, float* SSQ) {
;     for (int it = C.bid; it < NB * NH * 2; it += C.G) { const int half = it & 1, bh = it >> 1; scan_item(C, bh >> 4, bh & 15, half, HQ, LOGF, HI, SSQ); }
.LBB0_700:
	v_writelane_b32 v232, s83, 48
	v_writelane_b32 v232, s82, 49
	v_writelane_b32 v232, s78, 50
	s_nop 1
	v_writelane_b32 v232, s79, 51
	v_writelane_b32 v232, s75, 52
	v_writelane_b32 v232, s71, 53
	s_or_b64 exec, exec, s[0:1]
	s_add_u32 s82, s90, 0x800000
	s_addc_u32 s83, s91, 0
	s_cmpk_gt_i32 s74, 0xff
	v_writelane_b32 v232, s62, 54
	s_waitcnt lgkmcnt(0)
	s_barrier
	v_writelane_b32 v232, s63, 55
	s_cbranch_scc1 .LBB0_728
	s_cmp_eq_u32 s98, 0
	s_cbranch_scc1 .Lscan_prio_done
	s_setprio 1
.Lscan_prio_done:
	s_add_u32 s84, s90, 0x1e140000
	s_addc_u32 s85, s91, 0
	v_writelane_b32 v232, s70, 56
	s_bitcmp1_b32 s74, 0
	v_writelane_b32 v232, s92, 57
	s_cselect_b64 s[86:87], -1, 0
	s_bitcmp1_b32 s76, 0
	v_writelane_b32 v232, s93, 58
	s_cselect_b64 s[0:1], -1, 0
	v_writelane_b32 v232, s0, 59
	s_mov_b32 s59, 0
	v_mov_b32_e32 v0, 0
	v_writelane_b32 v232, s1, 60
	s_add_i32 s0, 0, 0xcc00
	v_writelane_b32 v232, s0, 61
	s_movk_i32 s93, 0x48
	s_movk_i32 s3, 0x88
	s_movk_i32 s33, 0x240
	v_mov_b32_e32 v69, 0x90
	v_mov_b32_e32 v108, 0x120
	v_mov_b32_e32 v109, 0x1b0
	s_mov_b32 s2, s74
	s_add_i32 s74, 0, 0x15800
	s_mov_b32 s0, 0x3fb8aa3b
	s_movk_i32 s75, 0x7fff
	s_add_i32 s92, 0, 0x17c00
	v_mbcnt_hi_u32_b32 v110, -1, v193
	v_writelane_b32 v232, s2, 62
	s_branch .LBB0_703

; __device__ __forceinline__ unsigned xb_ld(unsigned* p)              { return __hip_atomic_load(p, __ATOMIC_RELAXED, __HIP_MEMORY_SCOPE_AGENT); }
; __device__ __forceinline__ void xcd_barrier_complete(unsigned* bar, unsigned x, unsigned& nloc, unsigned& nx) {
;     const unsigned G = gridDim.x * gridDim.y * gridDim.z;
;     unsigned sum, cnt, mine, sp = 0u;
;     for (;;) {
;         sum = 0u; cnt = 0u; mine = 0u;
; #pragma unroll
;         for (unsigned j = 0; j < 16; ++j) { const unsigned c = xb_ld(&bar[XB_XCNT(j)]); sum += c; cnt += (c > 0u) ? 1u : 0u; mine = (j == x) ? c : mine; }
; __device__ __forceinline__ void xcd_barrier(const XcdBarrier& b) {
;     asm volatile("s_waitcnt vmcnt(0)" ::: "memory");
;     __syncthreads();
;     if (threadIdx.x == 0) {
;         unsigned* bar = b.bar;
;         __builtin_amdgcn_s_waitcnt(0);
;         unsigned nloc = b.st[0], nx = b.st[1];
;         if (nloc == 0u) { xcd_barrier_complete(bar, b.x, nloc, nx); b.st[0] = nloc; b.st[1] = nx; }
.LBB0_728:
	s_setprio 0
	s_waitcnt vmcnt(0)
	s_barrier
	s_mov_b64 s[0:1], exec
	v_readlane_b32 s2, v232, 50
	v_readlane_b32 s3, v232, 51
	s_and_b64 s[2:3], s[0:1], s[2:3]
	s_mov_b64 exec, s[2:3]
	s_cbranch_execz .LBB0_780
	s_add_i32 s2, 0, 0x20040
	v_mov_b32_e32 v0, s2
	s_waitcnt vmcnt(0) expcnt(0) lgkmcnt(0)
	ds_read_b32 v2, v0
	s_add_i32 s2, 0, 0x20044
	v_mov_b32_e32 v0, s2
	ds_read_b32 v0, v0
	s_waitcnt lgkmcnt(1)
	v_cmp_ne_u32_e32 vcc, 0, v2
	s_cbranch_vccnz .LBB0_744
	s_add_u32 s4, s90, 0x1200
	s_addc_u32 s5, s91, 0
	s_add_u32 s6, s90, 0x1400
	s_addc_u32 s7, s91, 0
	s_add_u32 s8, s90, 0x1500
	s_addc_u32 s9, s91, 0
	s_add_u32 s10, s90, 0x1600
	s_addc_u32 s11, s91, 0
	s_add_u32 s12, s90, 0x1700
	s_addc_u32 s13, s91, 0
	s_add_u32 s14, s90, 0x1800
	s_addc_u32 s15, s91, 0
	s_add_u32 s16, s90, 0x1900
	s_addc_u32 s17, s91, 0
	s_add_u32 s18, s90, 0x1a00
	s_addc_u32 s19, s91, 0
	s_add_u32 s20, s90, 0x1b00
	s_addc_u32 s21, s91, 0
	s_add_u32 s22, s90, 0x1c00
	s_addc_u32 s23, s91, 0
	s_add_u32 s24, s90, 0x1d00
	s_addc_u32 s25, s91, 0
	s_add_u32 s26, s90, 0x1e00
	s_addc_u32 s27, s91, 0
	s_add_u32 s28, s90, 0x1f00
	s_addc_u32 s29, s91, 0
	s_add_u32 s30, s90, 0x2000
	s_addc_u32 s31, s91, 0
	s_add_u32 s34, s90, 0x2100
	s_addc_u32 s35, s91, 0
	s_add_u32 s36, s90, 0x2200
	v_readlane_b32 s2, v232, 53
	s_addc_u32 s37, s91, 0
	s_mul_i32 s2, s77, s2
	s_add_u32 s38, s90, 0x2300
	s_mul_i32 s2, s2, s76
	s_addc_u32 s39, s91, 0
	s_mov_b32 s3, 1
	v_mov_b32_e32 v16, 0
	s_branch .LBB0_732
